# v31: GLA G3 gate-prefix and q~/k~ section hand-rewritten with batched LDS reads (3 waits instead of 42 round trips), same arithmetic
# speedup vs baseline: 1.0087x; 1.0087x over previous
.LBB0_133:
	s_or_b64 exec, exec, s[0:1]
	v_lshl_add_u64 v[2:3], s[30:31], 0, v[96:97]
	v_mov_b64_e32 v[0:1], s[6:7]
	v_mad_u64_u32 v[4:5], s[0:1], v2, s26, v[0:1]
	v_mov_b32_e32 v2, v5
	v_mad_u64_u32 v[2:3], s[0:1], v3, s26, v[2:3]
	v_mov_b32_e32 v5, v2
	s_lshl_b32 s0, s5, 9
	s_mov_b32 s1, s4
	v_lshl_add_u64 v[2:3], v[4:5], 0, s[0:1]
	v_mov_b32_e32 v115, v193
	v_lshl_add_u64 v[2:3], v[2:3], 0, v[114:115]
	global_load_dwordx4 v[232:235], v[2:3], off offset:2048
	s_ashr_i32 s11, s10, 31
	v_or_b32_e32 v138, s30, v88
	s_mul_i32 s5, s31, 0x1a00
	v_or_b32_e32 v128, s30, v108
	v_mov_b32_e32 v117, v193
	s_mov_b64 s[80:81], 0x1000
	v_mov_b32_e32 v139, s31
	v_mov_b32_e32 v129, s31
	v_add_u32_e32 v113, 0xb000, v165
	v_lshl_add_u64 v[2:3], s[30:31], 0, v[98:99]
	v_mad_u64_u32 v[4:5], s[24:25], v2, s26, v[0:1]
	v_mov_b32_e32 v2, v5
	v_mad_u64_u32 v[2:3], s[24:25], v3, s26, v[2:3]
	v_mov_b32_e32 v5, v2
	v_lshl_add_u64 v[2:3], v[4:5], 0, s[0:1]
	v_lshl_add_u64 v[2:3], v[2:3], 0, v[114:115]
	global_load_dwordx4 v[236:239], v[2:3], off offset:2048
	v_lshl_add_u64 v[2:3], s[30:31], 0, v[100:101]
	v_mad_u64_u32 v[4:5], s[24:25], v2, s26, v[0:1]
	v_mov_b32_e32 v2, v5
	v_mad_u64_u32 v[2:3], s[24:25], v3, s26, v[2:3]
	v_mov_b32_e32 v5, v2
	v_lshl_add_u64 v[2:3], v[4:5], 0, s[0:1]
	v_lshl_add_u64 v[2:3], v[2:3], 0, v[114:115]
	global_load_dwordx4 v[240:243], v[2:3], off offset:2048
	v_lshl_add_u64 v[2:3], s[30:31], 0, v[102:103]
	v_mad_u64_u32 v[4:5], s[24:25], v2, s26, v[0:1]
	v_mov_b32_e32 v2, v5
	v_mad_u64_u32 v[2:3], s[24:25], v3, s26, v[2:3]
	v_mov_b32_e32 v5, v2
	v_lshl_add_u64 v[2:3], v[4:5], 0, s[0:1]
	v_lshl_add_u64 v[2:3], v[2:3], 0, v[114:115]
	global_load_dwordx4 v[182:185], v[2:3], off offset:2048
	s_lshl_b64 s[24:25], s[10:11], 16
	s_movk_i32 s11, 0x1000
	s_mov_b64 s[30:31], s[64:65]
	v_add_u32_e32 v115, 0xb000, v166
	s_waitcnt vmcnt(0)
	ds_write_b128 v16, v[216:219]
	ds_write_b128 v17, v[220:223]
	ds_write_b128 v18, v[224:227]
	ds_write_b128 v19, v[228:231]
	ds_write_b128 v151, v[232:235] offset:8192
	ds_write_b128 v152, v[236:239] offset:8192
	ds_write_b128 v153, v[240:243] offset:8192
	ds_write_b128 v154, v[182:185] offset:8192
	v_cmp_gt_u32_e32 vcc, 0x80, v195
	s_and_saveexec_b64 s[100:101], vcc
	ds_write_b128 v150, v[186:189]
	s_or_b64 exec, exec, s[100:101]
	v_readfirstlane_b32 s100, v89
	s_lshr_b32 s100, s100, 1
	s_and_b32 s100, s100, 0x60
	v_or_b32_e32 v222, s3, v88
	v_or_b32_e32 v222, s100, v222
	v_lshlrev_b32_e32 v220, 5, v222
	v_mov_b32_e32 v221, v193
	v_lshl_add_u64 v[220:221], v[106:107], 0, v[220:221]
	global_load_dwordx4 v[216:219], v[220:221], off
	v_readlane_b32 s100, v245, 38
	v_readlane_b32 s101, v245, 39
	v_lshlrev_b32_e32 v222, 2, v222
	s_nop 4
	global_load_dword v223, v222, s[100:101]
	v_lshl_add_u64 v[2:3], v[104:105], 0, s[24:25]
	v_readlane_b32 s24, v245, 58
	v_readlane_b32 s25, v245, 59
	s_nop 1
	v_lshl_add_u64 v[4:5], v[2:3], 0, s[24:25]
	v_readlane_b32 s24, v245, 46
	v_readlane_b32 s25, v245, 47
	global_load_dwordx4 v[60:63], v[4:5], off
	s_nop 0
	v_lshl_add_u64 v[4:5], v[2:3], 0, s[24:25]
	v_readlane_b32 s24, v245, 48
	v_readlane_b32 s25, v245, 49
	global_load_dwordx4 v[56:59], v[4:5], off
	s_nop 0
	v_lshl_add_u64 v[4:5], v[2:3], 0, s[24:25]
	v_readlane_b32 s24, v245, 50
	v_readlane_b32 s25, v245, 51
	global_load_dwordx4 v[52:55], v[4:5], off
	s_nop 0
	v_lshl_add_u64 v[4:5], v[2:3], 0, s[24:25]
	v_readlane_b32 s24, v245, 52
	v_readlane_b32 s25, v245, 53
	global_load_dwordx4 v[48:51], v[4:5], off
	s_nop 0
	v_lshl_add_u64 v[4:5], v[2:3], 0, s[24:25]
	v_readlane_b32 s24, v245, 54
	v_readlane_b32 s25, v245, 55
	global_load_dwordx4 v[44:47], v[4:5], off
	s_nop 0
	v_lshl_add_u64 v[4:5], v[2:3], 0, s[24:25]
	v_readlane_b32 s24, v245, 56
	v_readlane_b32 s25, v245, 57
	global_load_dwordx4 v[40:43], v[4:5], off
	s_nop 0
	v_lshl_add_u64 v[4:5], v[2:3], 0, s[24:25]
	v_readlane_b32 s24, v245, 60
	v_readlane_b32 s25, v245, 61
	global_load_dwordx4 v[36:39], v[4:5], off
	s_nop 0
	v_lshl_add_u64 v[2:3], v[2:3], 0, s[24:25]
	global_load_dwordx4 v[32:35], v[2:3], off
	v_mad_u64_u32 v[2:3], s[24:25], v138, s26, v[0:1]
	v_add_u32_e32 v3, s5, v3
	v_lshl_add_u64 v[2:3], v[2:3], 0, s[0:1]
	v_mad_u64_u32 v[0:1], s[24:25], v128, s26, v[0:1]
	v_lshl_add_u64 v[2:3], v[2:3], 0, s[8:9]
	v_add_u32_e32 v1, s5, v1
	v_lshl_add_u64 v[2:3], v[2:3], 0, v[116:117]
	v_lshl_add_u64 v[0:1], v[0:1], 0, s[0:1]
	v_lshl_add_u64 v[4:5], v[2:3], 0, s[80:81]
	v_add_co_u32_e32 v2, vcc, s11, v2
	v_lshl_add_u64 v[0:1], v[0:1], 0, s[8:9]
	v_readfirstlane_b32 s0, v89
	v_addc_co_u32_e32 v3, vcc, 0, v3, vcc
	v_lshl_add_u64 v[0:1], v[0:1], 0, v[116:117]
	s_ashr_i32 s1, s0, 3
	s_lshr_b32 s0, s0, 1
	global_load_dwordx2 v[136:137], v[2:3], off
	global_load_dwordx2 v[134:135], v[4:5], off offset:16
	global_load_dwordx2 v[132:133], v[4:5], off offset:32
	global_load_dwordx2 v[130:131], v[4:5], off offset:48
	v_lshl_add_u64 v[2:3], v[0:1], 0, s[80:81]
	v_add_co_u32_e32 v0, vcc, s11, v0
	s_and_b32 s11, s0, 0x60
	v_or_b32_e32 v4, s3, v88
	v_or_b32_e32 v16, s11, v4
	v_lshlrev_b32_e32 v4, 5, v16
	v_mov_b32_e32 v5, v193
	v_addc_co_u32_e32 v1, vcc, 0, v1, vcc
	v_lshl_add_u64 v[4:5], v[106:107], 0, v[4:5]
	global_load_dwordx2 v[126:127], v[0:1], off
	global_load_dwordx2 v[124:125], v[2:3], off offset:16
	global_load_dwordx2 v[122:123], v[2:3], off offset:32
	global_load_dwordx2 v[120:121], v[2:3], off offset:48
	s_waitcnt lgkmcnt(0)
	s_barrier
	s_and_b32 s5, s1, 0xffffffe0
	v_readlane_b32 s0, v245, 38
	v_lshlrev_b32_e32 v16, 2, v16
	v_readlane_b32 s1, v245, 39
	v_or_b32_e32 v0, s5, v88
	v_lshl_add_u32 v0, v0, 5, v145
	ds_read_b128 v[0:3], v0
	s_mov_b32 s3, 0xbfb8aa3b
	s_mov_b32 s24, 0x3f317217
	s_mov_b32 s25, 0x7f800000
	s_waitcnt vmcnt(16) lgkmcnt(0)
	v_mfma_f32_32x32x16_bf16 v[0:15], v[0:3], v[216:219], 0
	v_mov_b32_e32 v16, v223
	s_nop 10
	v_add_f32_e32 v0, v16, v0
	v_min_f32_e32 v17, 0, v0
	v_mul_f32_e64 v0, |v0|, s3
	v_exp_f32_e32 v0, v0
	v_add_f32_e32 v1, v16, v1
	v_add_f32_e32 v0, 1.0, v0
	v_cmp_gt_f32_e32 vcc, s83, v0
	s_nop 1
	v_cndmask_b32_e64 v18, 0, 32, vcc
	v_ldexp_f32 v0, v0, v18
	v_log_f32_e32 v0, v0
	s_nop 0
	v_mul_f32_e32 v18, 0x3f317217, v0
	v_fma_f32 v18, v0, s24, -v18
	v_fmac_f32_e32 v18, 0x3377d1cf, v0
	v_fmac_f32_e32 v18, 0x3f317217, v0
	v_cmp_lt_f32_e64 s[0:1], |v0|, s25
	s_nop 1
	v_cndmask_b32_e64 v0, v0, v18, s[0:1]
	v_cndmask_b32_e32 v18, 0, v211, vcc
	v_sub_f32_e32 v0, v0, v18
	v_min_f32_e32 v18, 0, v1
	v_mul_f32_e64 v1, |v1|, s3
	v_exp_f32_e32 v1, v1
	s_lshl_b32 s0, s5, 9
	s_lshl_b32 s1, s11, 2
	v_sub_f32_e32 v0, v17, v0
	v_add_f32_e32 v1, 1.0, v1
	v_cmp_gt_f32_e32 vcc, s83, v1
	s_or_b32 s0, s0, s1
	v_mul_f32_e32 v17, 0x3d800000, v0
	v_cndmask_b32_e64 v19, 0, 32, vcc
	v_ldexp_f32 v1, v1, v19
	v_log_f32_e32 v1, v1
	v_add_u32_e32 v0, s0, v146
	v_mul_f32_e32 v19, 0x3f317217, v1
	v_fma_f32 v19, v1, s24, -v19
	v_fmac_f32_e32 v19, 0x3377d1cf, v1
	v_fmac_f32_e32 v19, 0x3f317217, v1
	v_cmp_lt_f32_e64 s[0:1], |v1|, s25
	s_nop 1
	v_cndmask_b32_e64 v1, v1, v19, s[0:1]
	v_cndmask_b32_e32 v19, 0, v211, vcc
	v_sub_f32_e32 v1, v1, v19
	v_sub_f32_e32 v1, v18, v1
	v_mul_f32_e32 v1, 0x3d800000, v1
	ds_write2st64_b32 v0, v17, v1 offset0:176 offset1:178
	v_add_f32_e32 v1, v16, v2
	v_min_f32_e32 v2, 0, v1
	v_mul_f32_e64 v1, |v1|, s3
	v_exp_f32_e32 v1, v1
	s_nop 0
	v_add_f32_e32 v1, 1.0, v1
	v_cmp_gt_f32_e32 vcc, s83, v1
	s_nop 1
	v_cndmask_b32_e64 v17, 0, 32, vcc
	v_ldexp_f32 v1, v1, v17
	v_log_f32_e32 v1, v1
	s_nop 0
	v_mul_f32_e32 v17, 0x3f317217, v1
	v_fma_f32 v17, v1, s24, -v17
	v_fmac_f32_e32 v17, 0x3377d1cf, v1
	v_fmac_f32_e32 v17, 0x3f317217, v1
	v_cmp_lt_f32_e64 s[0:1], |v1|, s25
	s_nop 1
	v_cndmask_b32_e64 v1, v1, v17, s[0:1]
	v_cndmask_b32_e32 v17, 0, v211, vcc
	v_sub_f32_e32 v1, v1, v17
	v_sub_f32_e32 v1, v2, v1
	v_add_f32_e32 v2, v16, v3
	v_min_f32_e32 v3, 0, v2
	v_mul_f32_e64 v2, |v2|, s3
	v_exp_f32_e32 v2, v2
	v_mul_f32_e32 v1, 0x3d800000, v1
	v_add_f32_e32 v2, 1.0, v2
	v_cmp_gt_f32_e32 vcc, s83, v2
	s_nop 1
	v_cndmask_b32_e64 v17, 0, 32, vcc
	v_ldexp_f32 v2, v2, v17
	v_log_f32_e32 v2, v2
	s_nop 0
	v_mul_f32_e32 v17, 0x3f317217, v2
	v_fma_f32 v17, v2, s24, -v17
	v_fmac_f32_e32 v17, 0x3377d1cf, v2
	v_fmac_f32_e32 v17, 0x3f317217, v2
	v_cmp_lt_f32_e64 s[0:1], |v2|, s25
	s_nop 1
	v_cndmask_b32_e64 v2, v2, v17, s[0:1]
	v_cndmask_b32_e32 v17, 0, v211, vcc
	v_sub_f32_e32 v2, v2, v17
	v_sub_f32_e32 v2, v3, v2
	v_mul_f32_e32 v2, 0x3d800000, v2
	ds_write2st64_b32 v0, v1, v2 offset0:180 offset1:182
	v_add_f32_e32 v1, v16, v4
	v_min_f32_e32 v2, 0, v1
	v_mul_f32_e64 v1, |v1|, s3
	v_exp_f32_e32 v1, v1
	s_nop 0
	v_add_f32_e32 v1, 1.0, v1
	v_cmp_gt_f32_e32 vcc, s83, v1
	s_nop 1
	v_cndmask_b32_e64 v3, 0, 32, vcc
	v_ldexp_f32 v1, v1, v3
	v_log_f32_e32 v1, v1
	s_nop 0
	v_mul_f32_e32 v3, 0x3f317217, v1
	v_fma_f32 v3, v1, s24, -v3
	v_fmac_f32_e32 v3, 0x3377d1cf, v1
	v_fmac_f32_e32 v3, 0x3f317217, v1
	v_cmp_lt_f32_e64 s[0:1], |v1|, s25
	s_nop 1
	v_cndmask_b32_e64 v1, v1, v3, s[0:1]
	v_cndmask_b32_e32 v3, 0, v211, vcc
	v_sub_f32_e32 v1, v1, v3
	v_sub_f32_e32 v1, v2, v1
	v_add_f32_e32 v2, v16, v5
	v_min_f32_e32 v3, 0, v2
	v_mul_f32_e64 v2, |v2|, s3
	v_exp_f32_e32 v2, v2
	v_mul_f32_e32 v1, 0x3d800000, v1
	v_add_f32_e32 v2, 1.0, v2
	v_cmp_gt_f32_e32 vcc, s83, v2
	s_nop 1
	v_cndmask_b32_e64 v4, 0, 32, vcc
	v_ldexp_f32 v2, v2, v4
	v_log_f32_e32 v2, v2
	s_nop 0
	v_mul_f32_e32 v4, 0x3f317217, v2
	v_fma_f32 v4, v2, s24, -v4
	v_fmac_f32_e32 v4, 0x3377d1cf, v2
	v_fmac_f32_e32 v4, 0x3f317217, v2
	v_cmp_lt_f32_e64 s[0:1], |v2|, s25
	s_nop 1
	v_cndmask_b32_e64 v2, v2, v4, s[0:1]
	v_cndmask_b32_e32 v4, 0, v211, vcc
	v_sub_f32_e32 v2, v2, v4
	v_sub_f32_e32 v2, v3, v2
	v_mul_f32_e32 v2, 0x3d800000, v2
	ds_write2st64_b32 v0, v1, v2 offset0:192 offset1:194
	v_add_f32_e32 v1, v16, v6
	v_min_f32_e32 v2, 0, v1
	v_mul_f32_e64 v1, |v1|, s3
	v_exp_f32_e32 v1, v1
	s_nop 0
	v_add_f32_e32 v1, 1.0, v1
	v_cmp_gt_f32_e32 vcc, s83, v1
	s_nop 1
	v_cndmask_b32_e64 v3, 0, 32, vcc
	v_ldexp_f32 v1, v1, v3
	v_log_f32_e32 v1, v1
	s_nop 0
	v_mul_f32_e32 v3, 0x3f317217, v1
	v_fma_f32 v3, v1, s24, -v3
	v_fmac_f32_e32 v3, 0x3377d1cf, v1
	v_fmac_f32_e32 v3, 0x3f317217, v1
	v_cmp_lt_f32_e64 s[0:1], |v1|, s25
	s_nop 1
	v_cndmask_b32_e64 v1, v1, v3, s[0:1]
	v_cndmask_b32_e32 v3, 0, v211, vcc
	v_sub_f32_e32 v1, v1, v3
	v_sub_f32_e32 v1, v2, v1
	v_add_f32_e32 v2, v16, v7
	v_min_f32_e32 v3, 0, v2
	v_mul_f32_e64 v2, |v2|, s3
	v_exp_f32_e32 v2, v2
	v_mul_f32_e32 v1, 0x3d800000, v1
	v_add_f32_e32 v2, 1.0, v2
	v_cmp_gt_f32_e32 vcc, s83, v2
	s_nop 1
	v_cndmask_b32_e64 v4, 0, 32, vcc
	v_ldexp_f32 v2, v2, v4
	v_log_f32_e32 v2, v2
	s_nop 0
	v_mul_f32_e32 v4, 0x3f317217, v2
	v_fma_f32 v4, v2, s24, -v4
	v_fmac_f32_e32 v4, 0x3377d1cf, v2
	v_fmac_f32_e32 v4, 0x3f317217, v2
	v_cmp_lt_f32_e64 s[0:1], |v2|, s25
	s_nop 1
	v_cndmask_b32_e64 v2, v2, v4, s[0:1]
	v_cndmask_b32_e32 v4, 0, v211, vcc
	v_sub_f32_e32 v2, v2, v4
	v_sub_f32_e32 v2, v3, v2
	v_mul_f32_e32 v2, 0x3d800000, v2
	ds_write2st64_b32 v0, v1, v2 offset0:196 offset1:198
	v_add_f32_e32 v1, v16, v8
	v_min_f32_e32 v2, 0, v1
	v_mul_f32_e64 v1, |v1|, s3
	v_exp_f32_e32 v1, v1
	s_nop 0
	v_add_f32_e32 v1, 1.0, v1
	v_cmp_gt_f32_e32 vcc, s83, v1
	s_nop 1
	v_cndmask_b32_e64 v3, 0, 32, vcc
	v_ldexp_f32 v1, v1, v3
	v_log_f32_e32 v1, v1
	s_nop 0
	v_mul_f32_e32 v3, 0x3f317217, v1
	v_fma_f32 v3, v1, s24, -v3
	v_fmac_f32_e32 v3, 0x3377d1cf, v1
	v_fmac_f32_e32 v3, 0x3f317217, v1
	v_cmp_lt_f32_e64 s[0:1], |v1|, s25
	s_nop 1
	v_cndmask_b32_e64 v1, v1, v3, s[0:1]
	v_cndmask_b32_e32 v3, 0, v211, vcc
	v_sub_f32_e32 v1, v1, v3
	v_sub_f32_e32 v1, v2, v1
	v_add_f32_e32 v2, v16, v9
	v_min_f32_e32 v3, 0, v2
	v_mul_f32_e64 v2, |v2|, s3
	v_exp_f32_e32 v2, v2
	v_mul_f32_e32 v1, 0x3d800000, v1
	v_add_f32_e32 v2, 1.0, v2
	v_cmp_gt_f32_e32 vcc, s83, v2
	s_nop 1
	v_cndmask_b32_e64 v4, 0, 32, vcc
	v_ldexp_f32 v2, v2, v4
	v_log_f32_e32 v2, v2
	s_nop 0
	v_mul_f32_e32 v4, 0x3f317217, v2
	v_fma_f32 v4, v2, s24, -v4
	v_fmac_f32_e32 v4, 0x3377d1cf, v2
	v_fmac_f32_e32 v4, 0x3f317217, v2
	v_cmp_lt_f32_e64 s[0:1], |v2|, s25
	s_nop 1
	v_cndmask_b32_e64 v2, v2, v4, s[0:1]
	v_cndmask_b32_e32 v4, 0, v211, vcc
	v_sub_f32_e32 v2, v2, v4
	v_sub_f32_e32 v2, v3, v2
	v_mul_f32_e32 v2, 0x3d800000, v2
	ds_write2st64_b32 v0, v1, v2 offset0:208 offset1:210
	v_add_f32_e32 v1, v16, v10
	v_min_f32_e32 v2, 0, v1
	v_mul_f32_e64 v1, |v1|, s3
	v_exp_f32_e32 v1, v1
	s_nop 0
	v_add_f32_e32 v1, 1.0, v1
	v_cmp_gt_f32_e32 vcc, s83, v1
	s_nop 1
	v_cndmask_b32_e64 v3, 0, 32, vcc
	v_ldexp_f32 v1, v1, v3
	v_log_f32_e32 v1, v1
	s_nop 0
	v_mul_f32_e32 v3, 0x3f317217, v1
	v_fma_f32 v3, v1, s24, -v3
	v_fmac_f32_e32 v3, 0x3377d1cf, v1
	v_fmac_f32_e32 v3, 0x3f317217, v1
	v_cmp_lt_f32_e64 s[0:1], |v1|, s25
	s_nop 1
	v_cndmask_b32_e64 v1, v1, v3, s[0:1]
	v_cndmask_b32_e32 v3, 0, v211, vcc
	v_sub_f32_e32 v1, v1, v3
	v_sub_f32_e32 v1, v2, v1
	v_add_f32_e32 v2, v16, v11
	v_min_f32_e32 v3, 0, v2
	v_mul_f32_e64 v2, |v2|, s3
	v_exp_f32_e32 v2, v2
	v_mul_f32_e32 v1, 0x3d800000, v1
	v_add_f32_e32 v2, 1.0, v2
	v_cmp_gt_f32_e32 vcc, s83, v2
	s_nop 1
	v_cndmask_b32_e64 v4, 0, 32, vcc
	v_ldexp_f32 v2, v2, v4
	v_log_f32_e32 v2, v2
	s_nop 0
	v_mul_f32_e32 v4, 0x3f317217, v2
	v_fma_f32 v4, v2, s24, -v4
	v_fmac_f32_e32 v4, 0x3377d1cf, v2
	v_fmac_f32_e32 v4, 0x3f317217, v2
	v_cmp_lt_f32_e64 s[0:1], |v2|, s25
	s_nop 1
	v_cndmask_b32_e64 v2, v2, v4, s[0:1]
	v_cndmask_b32_e32 v4, 0, v211, vcc
	v_sub_f32_e32 v2, v2, v4
	v_sub_f32_e32 v2, v3, v2
	v_mul_f32_e32 v2, 0x3d800000, v2
	ds_write2st64_b32 v0, v1, v2 offset0:212 offset1:214
	v_add_f32_e32 v1, v16, v12
	v_min_f32_e32 v2, 0, v1
	v_mul_f32_e64 v1, |v1|, s3
	v_exp_f32_e32 v1, v1
	s_nop 0
	v_add_f32_e32 v1, 1.0, v1
	v_cmp_gt_f32_e32 vcc, s83, v1
	s_nop 1
	v_cndmask_b32_e64 v3, 0, 32, vcc
	v_ldexp_f32 v1, v1, v3
	v_log_f32_e32 v1, v1
	s_nop 0
	v_mul_f32_e32 v3, 0x3f317217, v1
	v_fma_f32 v3, v1, s24, -v3
	v_fmac_f32_e32 v3, 0x3377d1cf, v1
	v_fmac_f32_e32 v3, 0x3f317217, v1
	v_cmp_lt_f32_e64 s[0:1], |v1|, s25
	s_nop 1
	v_cndmask_b32_e64 v1, v1, v3, s[0:1]
	v_cndmask_b32_e32 v3, 0, v211, vcc
	v_sub_f32_e32 v1, v1, v3
	v_sub_f32_e32 v1, v2, v1
	v_add_f32_e32 v2, v16, v13
	v_min_f32_e32 v3, 0, v2
	v_mul_f32_e64 v2, |v2|, s3
	v_exp_f32_e32 v2, v2
	v_mul_f32_e32 v1, 0x3d800000, v1
	v_add_f32_e32 v2, 1.0, v2
	v_cmp_gt_f32_e32 vcc, s83, v2
	s_nop 1
	v_cndmask_b32_e64 v4, 0, 32, vcc
	v_ldexp_f32 v2, v2, v4
	v_log_f32_e32 v2, v2
	s_nop 0
	v_mul_f32_e32 v4, 0x3f317217, v2
	v_fma_f32 v4, v2, s24, -v4
	v_fmac_f32_e32 v4, 0x3377d1cf, v2
	v_fmac_f32_e32 v4, 0x3f317217, v2
	v_cmp_lt_f32_e64 s[0:1], |v2|, s25
	s_nop 1
	v_cndmask_b32_e64 v2, v2, v4, s[0:1]
	v_cndmask_b32_e32 v4, 0, v211, vcc
	v_sub_f32_e32 v2, v2, v4
	v_sub_f32_e32 v2, v3, v2
	v_mul_f32_e32 v2, 0x3d800000, v2
	ds_write2st64_b32 v0, v1, v2 offset0:224 offset1:226
	v_add_f32_e32 v1, v16, v14
	v_min_f32_e32 v2, 0, v1
	v_mul_f32_e64 v1, |v1|, s3
	v_exp_f32_e32 v1, v1
	s_nop 0
	v_add_f32_e32 v1, 1.0, v1
	v_cmp_gt_f32_e32 vcc, s83, v1
	s_nop 1
	v_cndmask_b32_e64 v3, 0, 32, vcc
	v_ldexp_f32 v1, v1, v3
	v_log_f32_e32 v1, v1
	s_nop 0
	v_mul_f32_e32 v3, 0x3f317217, v1
	v_fma_f32 v3, v1, s24, -v3
	v_fmac_f32_e32 v3, 0x3377d1cf, v1
	v_fmac_f32_e32 v3, 0x3f317217, v1
	v_cmp_lt_f32_e64 s[0:1], |v1|, s25
	s_nop 1
	v_cndmask_b32_e64 v1, v1, v3, s[0:1]
	v_cndmask_b32_e32 v3, 0, v211, vcc
	v_sub_f32_e32 v1, v1, v3
	v_sub_f32_e32 v1, v2, v1
	v_add_f32_e32 v2, v16, v15
	v_min_f32_e32 v3, 0, v2
	v_mul_f32_e64 v2, |v2|, s3
	v_exp_f32_e32 v2, v2
	v_mul_f32_e32 v1, 0x3d800000, v1
	v_add_f32_e32 v2, 1.0, v2
	v_cmp_gt_f32_e32 vcc, s83, v2
	s_nop 1
	v_cndmask_b32_e64 v4, 0, 32, vcc
	v_ldexp_f32 v2, v2, v4
	v_log_f32_e32 v2, v2
	s_nop 0
	v_mul_f32_e32 v4, 0x3f317217, v2
	v_fma_f32 v4, v2, s24, -v4
	v_fmac_f32_e32 v4, 0x3377d1cf, v2
	v_fmac_f32_e32 v4, 0x3f317217, v2
	v_cmp_lt_f32_e64 s[0:1], |v2|, s25
	v_readlane_b32 s24, v244, 0
	v_readlane_b32 s25, v244, 1
	v_cndmask_b32_e64 v2, v2, v4, s[0:1]
	v_cndmask_b32_e32 v4, 0, v211, vcc
	v_sub_f32_e32 v2, v2, v4
	v_sub_f32_e32 v2, v3, v2
	v_mul_f32_e32 v2, 0x3d800000, v2
	ds_write2st64_b32 v0, v1, v2 offset0:228 offset1:230
	s_waitcnt lgkmcnt(0)
	s_barrier
	s_waitcnt vmcnt(0)
	ds_read2st64_b32 v[216:217], v155 offset0:176 offset1:178
	ds_read2st64_b32 v[218:219], v155 offset0:180 offset1:182
	ds_read2st64_b32 v[220:221], v155 offset0:184 offset1:186
	ds_read2st64_b32 v[222:223], v155 offset0:188 offset1:190
	ds_read2st64_b32 v[224:225], v155 offset0:192 offset1:194
	ds_read2st64_b32 v[226:227], v155 offset0:196 offset1:198
	ds_read2st64_b32 v[228:229], v155 offset0:200 offset1:202
	ds_read2st64_b32 v[230:231], v155 offset0:204 offset1:206
	ds_read_u16 v232, v157
	ds_read_u16 v233, v158
	ds_read_u16 v234, v157 offset:256
	ds_read_u16 v235, v158 offset:256
	ds_read_u16 v236, v157 offset:512
	ds_read_u16 v237, v158 offset:512
	ds_read_u16 v238, v157 offset:768
	ds_read_u16 v239, v158 offset:768
	ds_read_u16 v240, v157 offset:1024
	ds_read_u16 v241, v158 offset:1024
	ds_read_u16 v242, v157 offset:1280
	ds_read_u16 v243, v158 offset:1280
	ds_read_u16 v182, v157 offset:1536
	ds_read_u16 v183, v158 offset:1536
	ds_read_u16 v184, v157 offset:1792
	ds_read_u16 v185, v158 offset:1792
	v_readlane_b32 s0, v245, 36
	v_readlane_b32 s1, v245, 37
	s_waitcnt lgkmcnt(15)
	v_add_f32_e32 v2, 0, v216
	v_add_f32_e32 v3, v2, v217
	v_add_f32_e32 v4, v3, v218
	v_add_f32_e32 v5, v4, v219
	v_add_f32_e32 v6, v5, v220
	v_add_f32_e32 v7, v6, v221
	v_add_f32_e32 v8, v7, v222
	v_add_f32_e32 v9, v8, v223
	v_add_f32_e32 v10, v9, v224
	v_add_f32_e32 v11, v10, v225
	v_add_f32_e32 v12, v11, v226
	v_add_f32_e32 v13, v12, v227
	v_add_f32_e32 v14, v13, v228
	v_add_f32_e32 v15, v14, v229
	v_add_f32_e32 v16, v15, v230
	v_add_f32_e32 v17, v16, v231
	ds_write_b32 v156, v17 offset:4096
	s_waitcnt lgkmcnt(0)
	s_barrier
	ds_read2st64_b32 v[0:1], v140 offset0:16 offset1:18
	ds_read2st64_b32 v[20:21], v140 offset0:20 offset1:22
	ds_read_u16 v216, v157 offset:2048
	ds_read_u16 v217, v158 offset:2048
	ds_read_u16 v218, v157 offset:2304
	ds_read_u16 v219, v158 offset:2304
	ds_read_u16 v220, v157 offset:2560
	ds_read_u16 v221, v158 offset:2560
	ds_read_u16 v222, v157 offset:2816
	ds_read_u16 v223, v158 offset:2816
	ds_read_u16 v224, v157 offset:3072
	ds_read_u16 v225, v158 offset:3072
	ds_read_u16 v226, v157 offset:3328
	ds_read_u16 v227, v158 offset:3328
	ds_read_u16 v228, v157 offset:3584
	ds_read_u16 v229, v158 offset:3584
	ds_read_u16 v230, v157 offset:3840
	ds_read_u16 v231, v158 offset:3840
	s_waitcnt lgkmcnt(15)
	v_add_f32_e32 v0, 0, v0
	v_cndmask_b32_e64 v0, 0, v0, s[0:1]
	v_readlane_b32 s0, v245, 31
	v_add_f32_e32 v1, v1, v0
	v_readlane_b32 s1, v245, 32
	s_nop 1
	v_cndmask_b32_e64 v18, v0, v1, s[0:1]
	v_readlane_b32 s0, v245, 40
	v_readlane_b32 s1, v245, 41
	v_add_f32_e32 v0, v20, v18
	s_nop 1
	v_cndmask_b32_e64 v0, v18, v0, s[0:1]
	v_readlane_b32 s0, v245, 42
	v_add_f32_e32 v1, v21, v0
	v_readlane_b32 s1, v245, 43
	s_nop 1
	v_cndmask_b32_e64 v0, v0, v1, s[0:1]
	s_movk_i32 s0, 0x7fff
	v_add_u32_e32 v1, v147, v149
	v_add_f32_e32 v2, v2, v0
	v_mul_f32_e32 v18, 0x3fb8aa3b, v2
	v_mul_f32_e32 v19, 0xbfb8aa3b, v2
	v_exp_f32_e32 v18, v18
	v_exp_f32_e32 v19, v19
	v_lshlrev_b32_e32 v232, 16, v232
	v_lshlrev_b32_e32 v233, 16, v233
	v_mul_f32_e32 v232, 0x3db504f3, v232
	v_mul_f32_e32 v232, v18, v232
	v_mul_f32_e32 v233, v19, v233
	v_bfe_u32 v20, v232, 16, 1
	v_bfe_u32 v21, v233, 16, 1
	v_add3_u32 v232, v232, v20, s0
	v_add3_u32 v233, v233, v21, s0
	ds_write_b16_d16_hi v1, v232 offset:45056
	ds_write_b16_d16_hi v1, v233 offset:62464
	v_add_f32_e32 v3, v3, v0
	v_mul_f32_e32 v18, 0x3fb8aa3b, v3
	v_mul_f32_e32 v19, 0xbfb8aa3b, v3
	v_exp_f32_e32 v18, v18
	v_exp_f32_e32 v19, v19
	v_lshlrev_b32_e32 v234, 16, v234
	v_lshlrev_b32_e32 v235, 16, v235
	v_mul_f32_e32 v234, 0x3db504f3, v234
	v_mul_f32_e32 v234, v18, v234
	v_mul_f32_e32 v235, v19, v235
	v_bfe_u32 v20, v234, 16, 1
	v_bfe_u32 v21, v235, 16, 1
	v_add3_u32 v234, v234, v20, s0
	v_add3_u32 v235, v235, v21, s0
	ds_write_b16_d16_hi v1, v234 offset:45328
	ds_write_b16_d16_hi v1, v235 offset:62736
	v_add_f32_e32 v4, v4, v0
	v_mul_f32_e32 v18, 0x3fb8aa3b, v4
	v_mul_f32_e32 v19, 0xbfb8aa3b, v4
	v_exp_f32_e32 v18, v18
	v_exp_f32_e32 v19, v19
	v_lshlrev_b32_e32 v236, 16, v236
	v_lshlrev_b32_e32 v237, 16, v237
	v_mul_f32_e32 v236, 0x3db504f3, v236
	v_mul_f32_e32 v236, v18, v236
	v_mul_f32_e32 v237, v19, v237
	v_bfe_u32 v20, v236, 16, 1
	v_bfe_u32 v21, v237, 16, 1
	v_add3_u32 v236, v236, v20, s0
	v_add3_u32 v237, v237, v21, s0
	ds_write_b16_d16_hi v1, v236 offset:45600
	ds_write_b16_d16_hi v1, v237 offset:63008
	v_add_f32_e32 v5, v5, v0
	v_mul_f32_e32 v18, 0x3fb8aa3b, v5
	v_mul_f32_e32 v19, 0xbfb8aa3b, v5
	v_exp_f32_e32 v18, v18
	v_exp_f32_e32 v19, v19
	v_lshlrev_b32_e32 v238, 16, v238
	v_lshlrev_b32_e32 v239, 16, v239
	v_mul_f32_e32 v238, 0x3db504f3, v238
	v_mul_f32_e32 v238, v18, v238
	v_mul_f32_e32 v239, v19, v239
	v_bfe_u32 v20, v238, 16, 1
	v_bfe_u32 v21, v239, 16, 1
	v_add3_u32 v238, v238, v20, s0
	v_add3_u32 v239, v239, v21, s0
	ds_write_b16_d16_hi v1, v238 offset:45872
	ds_write_b16_d16_hi v1, v239 offset:63280
	v_add_f32_e32 v6, v6, v0
	v_mul_f32_e32 v18, 0x3fb8aa3b, v6
	v_mul_f32_e32 v19, 0xbfb8aa3b, v6
	v_exp_f32_e32 v18, v18
	v_exp_f32_e32 v19, v19
	v_lshlrev_b32_e32 v240, 16, v240
	v_lshlrev_b32_e32 v241, 16, v241
	v_mul_f32_e32 v240, 0x3db504f3, v240
	v_mul_f32_e32 v240, v18, v240
	v_mul_f32_e32 v241, v19, v241
	v_bfe_u32 v20, v240, 16, 1
	v_bfe_u32 v21, v241, 16, 1
	v_add3_u32 v240, v240, v20, s0
	v_add3_u32 v241, v241, v21, s0
	ds_write_b16_d16_hi v1, v240 offset:46144
	ds_write_b16_d16_hi v1, v241 offset:63552
	v_add_f32_e32 v7, v7, v0
	v_mul_f32_e32 v18, 0x3fb8aa3b, v7
	v_mul_f32_e32 v19, 0xbfb8aa3b, v7
	v_exp_f32_e32 v18, v18
	v_exp_f32_e32 v19, v19
	v_lshlrev_b32_e32 v242, 16, v242
	v_lshlrev_b32_e32 v243, 16, v243
	v_mul_f32_e32 v242, 0x3db504f3, v242
	v_mul_f32_e32 v242, v18, v242
	v_mul_f32_e32 v243, v19, v243
	v_bfe_u32 v20, v242, 16, 1
	v_bfe_u32 v21, v243, 16, 1
	v_add3_u32 v242, v242, v20, s0
	v_add3_u32 v243, v243, v21, s0
	ds_write_b16_d16_hi v1, v242 offset:46416
	ds_write_b16_d16_hi v1, v243 offset:63824
	v_add_f32_e32 v8, v8, v0
	v_mul_f32_e32 v18, 0x3fb8aa3b, v8
	v_mul_f32_e32 v19, 0xbfb8aa3b, v8
	v_exp_f32_e32 v18, v18
	v_exp_f32_e32 v19, v19
	v_lshlrev_b32_e32 v182, 16, v182
	v_lshlrev_b32_e32 v183, 16, v183
	v_mul_f32_e32 v182, 0x3db504f3, v182
	v_mul_f32_e32 v182, v18, v182
	v_mul_f32_e32 v183, v19, v183
	v_bfe_u32 v20, v182, 16, 1
	v_bfe_u32 v21, v183, 16, 1
	v_add3_u32 v182, v182, v20, s0
	v_add3_u32 v183, v183, v21, s0
	ds_write_b16_d16_hi v1, v182 offset:46688
	ds_write_b16_d16_hi v1, v183 offset:64096
	v_add_f32_e32 v9, v9, v0
	v_mul_f32_e32 v18, 0x3fb8aa3b, v9
	v_mul_f32_e32 v19, 0xbfb8aa3b, v9
	v_exp_f32_e32 v18, v18
	v_exp_f32_e32 v19, v19
	v_lshlrev_b32_e32 v184, 16, v184
	v_lshlrev_b32_e32 v185, 16, v185
	v_mul_f32_e32 v184, 0x3db504f3, v184
	v_mul_f32_e32 v184, v18, v184
	v_mul_f32_e32 v185, v19, v185
	v_bfe_u32 v20, v184, 16, 1
	v_bfe_u32 v21, v185, 16, 1
	v_add3_u32 v184, v184, v20, s0
	v_add3_u32 v185, v185, v21, s0
	ds_write_b16_d16_hi v1, v184 offset:46960
	ds_write_b16_d16_hi v1, v185 offset:64368
	s_waitcnt lgkmcnt(15)
	v_add_f32_e32 v10, v10, v0
	v_mul_f32_e32 v18, 0x3fb8aa3b, v10
	v_mul_f32_e32 v19, 0xbfb8aa3b, v10
	v_exp_f32_e32 v18, v18
	v_exp_f32_e32 v19, v19
	v_lshlrev_b32_e32 v216, 16, v216
	v_lshlrev_b32_e32 v217, 16, v217
	v_mul_f32_e32 v216, 0x3db504f3, v216
	v_mul_f32_e32 v216, v18, v216
	v_mul_f32_e32 v217, v19, v217
	v_bfe_u32 v20, v216, 16, 1
	v_bfe_u32 v21, v217, 16, 1
	v_add3_u32 v216, v216, v20, s0
	v_add3_u32 v217, v217, v21, s0
	ds_write_b16_d16_hi v1, v216 offset:47232
	ds_write_b16_d16_hi v1, v217 offset:64640
	v_add_f32_e32 v11, v11, v0
	v_mul_f32_e32 v18, 0x3fb8aa3b, v11
	v_mul_f32_e32 v19, 0xbfb8aa3b, v11
	v_exp_f32_e32 v18, v18
	v_exp_f32_e32 v19, v19
	v_lshlrev_b32_e32 v218, 16, v218
	v_lshlrev_b32_e32 v219, 16, v219
	v_mul_f32_e32 v218, 0x3db504f3, v218
	v_mul_f32_e32 v218, v18, v218
	v_mul_f32_e32 v219, v19, v219
	v_bfe_u32 v20, v218, 16, 1
	v_bfe_u32 v21, v219, 16, 1
	v_add3_u32 v218, v218, v20, s0
	v_add3_u32 v219, v219, v21, s0
	ds_write_b16_d16_hi v1, v218 offset:47504
	ds_write_b16_d16_hi v1, v219 offset:64912
	v_add_f32_e32 v12, v12, v0
	v_mul_f32_e32 v18, 0x3fb8aa3b, v12
	v_mul_f32_e32 v19, 0xbfb8aa3b, v12
	v_exp_f32_e32 v18, v18
	v_exp_f32_e32 v19, v19
	v_lshlrev_b32_e32 v220, 16, v220
	v_lshlrev_b32_e32 v221, 16, v221
	v_mul_f32_e32 v220, 0x3db504f3, v220
	v_mul_f32_e32 v220, v18, v220
	v_mul_f32_e32 v221, v19, v221
	v_bfe_u32 v20, v220, 16, 1
	v_bfe_u32 v21, v221, 16, 1
	v_add3_u32 v220, v220, v20, s0
	v_add3_u32 v221, v221, v21, s0
	ds_write_b16_d16_hi v1, v220 offset:47776
	ds_write_b16_d16_hi v1, v221 offset:65184
	v_add_f32_e32 v13, v13, v0
	v_mul_f32_e32 v18, 0x3fb8aa3b, v13
	v_mul_f32_e32 v19, 0xbfb8aa3b, v13
	v_exp_f32_e32 v18, v18
	v_exp_f32_e32 v19, v19
	v_lshlrev_b32_e32 v222, 16, v222
	v_lshlrev_b32_e32 v223, 16, v223
	v_mul_f32_e32 v222, 0x3db504f3, v222
	v_mul_f32_e32 v222, v18, v222
	v_mul_f32_e32 v223, v19, v223
	v_bfe_u32 v20, v222, 16, 1
	v_bfe_u32 v21, v223, 16, 1
	v_add3_u32 v222, v222, v20, s0
	v_add3_u32 v223, v223, v21, s0
	ds_write_b16_d16_hi v1, v222 offset:48048
	ds_write_b16_d16_hi v1, v223 offset:65456
	v_add_f32_e32 v14, v14, v0
	v_mul_f32_e32 v18, 0x3fb8aa3b, v14
	v_mul_f32_e32 v19, 0xbfb8aa3b, v14
	v_exp_f32_e32 v18, v18
	v_exp_f32_e32 v19, v19
	v_lshlrev_b32_e32 v224, 16, v224
	v_lshlrev_b32_e32 v225, 16, v225
	v_mul_f32_e32 v224, 0x3db504f3, v224
	v_mul_f32_e32 v224, v18, v224
	v_mul_f32_e32 v225, v19, v225
	v_bfe_u32 v20, v224, 16, 1
	v_bfe_u32 v21, v225, 16, 1
	v_add3_u32 v224, v224, v20, s0
	v_add3_u32 v225, v225, v21, s0
	ds_write_b16_d16_hi v1, v224 offset:48320
	ds_write_b16_d16_hi v159, v225 offset:62464
	v_add_f32_e32 v15, v15, v0
	v_mul_f32_e32 v18, 0x3fb8aa3b, v15
	v_mul_f32_e32 v19, 0xbfb8aa3b, v15
	v_exp_f32_e32 v18, v18
	v_exp_f32_e32 v19, v19
	v_lshlrev_b32_e32 v226, 16, v226
	v_lshlrev_b32_e32 v227, 16, v227
	v_mul_f32_e32 v226, 0x3db504f3, v226
	v_mul_f32_e32 v226, v18, v226
	v_mul_f32_e32 v227, v19, v227
	v_bfe_u32 v20, v226, 16, 1
	v_bfe_u32 v21, v227, 16, 1
	v_add3_u32 v226, v226, v20, s0
	v_add3_u32 v227, v227, v21, s0
	ds_write_b16_d16_hi v1, v226 offset:48592
	ds_write_b16_d16_hi v160, v227 offset:62464
	v_add_f32_e32 v16, v16, v0
	v_mul_f32_e32 v18, 0x3fb8aa3b, v16
	v_mul_f32_e32 v19, 0xbfb8aa3b, v16
	v_exp_f32_e32 v18, v18
	v_exp_f32_e32 v19, v19
	v_lshlrev_b32_e32 v228, 16, v228
	v_lshlrev_b32_e32 v229, 16, v229
	v_mul_f32_e32 v228, 0x3db504f3, v228
	v_mul_f32_e32 v228, v18, v228
	v_mul_f32_e32 v229, v19, v229
	v_bfe_u32 v20, v228, 16, 1
	v_bfe_u32 v21, v229, 16, 1
	v_add3_u32 v228, v228, v20, s0
	v_add3_u32 v229, v229, v21, s0
	ds_write_b16_d16_hi v1, v228 offset:48864
	ds_write_b16_d16_hi v161, v229 offset:62464
	v_add_f32_e32 v17, v17, v0
	v_mul_f32_e32 v18, 0x3fb8aa3b, v17
	v_mul_f32_e32 v19, 0xbfb8aa3b, v17
	v_exp_f32_e32 v18, v18
	v_exp_f32_e32 v19, v19
	v_lshlrev_b32_e32 v230, 16, v230
	v_lshlrev_b32_e32 v231, 16, v231
	v_mul_f32_e32 v230, 0x3db504f3, v230
	v_mul_f32_e32 v230, v18, v230
	v_mul_f32_e32 v231, v19, v231
	v_bfe_u32 v20, v230, 16, 1
	v_bfe_u32 v21, v231, 16, 1
	v_add3_u32 v230, v230, v20, s0
	v_add3_u32 v231, v231, v21, s0
	ds_write_b16_d16_hi v1, v230 offset:49136
	ds_write_b16_d16_hi v162, v231 offset:62464
	s_waitcnt lgkmcnt(0)
	s_barrier
	ds_read_b128 v[16:19], v163 offset:62464
	ds_read_b128 v[0:3], v163 offset:45056
	ds_read_b128 v[20:23], v163 offset:45088
	ds_read_b128 v[24:27], v163 offset:62496
	s_waitcnt lgkmcnt(2)
	v_mfma_f32_32x32x16_bf16 v[0:15], v[16:19], v[0:3], 0
	v_readlane_b32 s0, v245, 62
	v_readlane_b32 s1, v245, 63
	s_waitcnt lgkmcnt(0)
	v_mfma_f32_32x32x16_bf16 v[0:15], v[24:27], v[20:23], v[0:15]
	ds_read_b128 v[20:23], v163 offset:62528
	ds_read_b128 v[28:31], v163 offset:45120
	s_waitcnt lgkmcnt(0)
	v_mfma_f32_32x32x16_bf16 v[0:15], v[20:23], v[28:31], v[0:15]
	ds_read_b128 v[28:31], v163 offset:62560
	ds_read_b128 v[64:67], v163 offset:45152
	s_waitcnt lgkmcnt(0)
	v_mfma_f32_32x32x16_bf16 v[0:15], v[28:31], v[64:67], v[0:15]
	ds_read_b128 v[72:75], v163 offset:62592
	ds_read_b128 v[64:67], v163 offset:45184
	s_waitcnt lgkmcnt(0)
	v_mfma_f32_32x32x16_bf16 v[0:15], v[72:75], v[64:67], v[0:15]
	ds_read_b128 v[76:79], v163 offset:62624
	ds_read_b128 v[64:67], v163 offset:45216
	s_waitcnt lgkmcnt(0)
	v_mfma_f32_32x32x16_bf16 v[0:15], v[76:79], v[64:67], v[0:15]
	ds_read_b128 v[80:83], v163 offset:62656
	ds_read_b128 v[64:67], v163 offset:45248
	s_waitcnt lgkmcnt(0)
	v_mfma_f32_32x32x16_bf16 v[0:15], v[80:83], v[64:67], v[0:15]
	ds_read_b128 v[84:87], v163 offset:62688
	ds_read_b128 v[64:67], v163 offset:45280
	ds_read_b128 v[170:173], v164 offset:45056
	ds_read_b128 v[174:177], v164 offset:45088
	ds_read_b128 v[178:181], v164 offset:45280
	s_waitcnt lgkmcnt(3)
	v_mfma_f32_32x32x16_bf16 v[0:15], v[84:87], v[64:67], v[0:15]
	s_nop 11
	v_cndmask_b32_e64 v64, v0, 0, s[78:79]
	v_cndmask_b32_e64 v0, v64, v0, s[76:77]
	v_cndmask_b32_e64 v1, 0, v1, s[76:77]
	v_cndmask_b32_e64 v2, v2, 0, s[74:75]
	v_cndmask_b32_e64 v3, v3, 0, s[46:47]
	v_cndmask_b32_e64 v4, v4, 0, s[44:45]
	v_cndmask_b32_e64 v5, v5, 0, s[42:43]
	v_cndmask_b32_e64 v6, v6, 0, s[38:39]
	v_cndmask_b32_e64 v7, v7, 0, s[36:37]
	v_cndmask_b32_e64 v8, v8, 0, s[40:41]
	v_cndmask_b32_e64 v9, v9, 0, s[18:19]
	v_cndmask_b32_e64 v10, v10, 0, s[16:17]
	v_cndmask_b32_e64 v11, v11, 0, s[14:15]
	v_cndmask_b32_e64 v12, v12, 0, s[12:13]
	v_cndmask_b32_e64 v13, v13, 0, s[30:31]
	v_cndmask_b32_e64 v14, v14, 0, s[24:25]
	v_cndmask_b32_e64 v15, v15, 0, s[0:1]
	v_cvt_pk_bf16_f32 v68, v0, v1
	v_cvt_pk_bf16_f32 v69, v2, v3
	v_cvt_pk_bf16_f32 v70, v4, v5
	v_cvt_pk_bf16_f32 v71, v6, v7
	v_cvt_pk_bf16_f32 v64, v8, v9
	v_cvt_pk_bf16_f32 v65, v10, v11
	v_cvt_pk_bf16_f32 v66, v12, v13
	v_cvt_pk_bf16_f32 v67, v14, v15
	s_waitcnt lgkmcnt(2)
	v_mfma_f32_32x32x16_bf16 v[0:15], v[16:19], v[170:173], 0
	ds_read_b128 v[16:19], v164 offset:45120
	s_waitcnt lgkmcnt(2)
	v_mfma_f32_32x32x16_bf16 v[0:15], v[24:27], v[174:177], v[0:15]
	ds_read_b128 v[24:27], v164 offset:45184
	s_waitcnt lgkmcnt(1)
	v_mfma_f32_32x32x16_bf16 v[0:15], v[20:23], v[16:19], v[0:15]
	ds_read_b128 v[20:23], v164 offset:45152
	s_waitcnt lgkmcnt(0)
	v_mfma_f32_32x32x16_bf16 v[0:15], v[28:31], v[20:23], v[0:15]
	ds_read_b128 v[28:31], v164 offset:45216
	v_mfma_f32_32x32x16_bf16 v[0:15], v[72:75], v[24:27], v[0:15]
	ds_read_b128 v[72:75], v164 offset:45248
	s_waitcnt lgkmcnt(1)
	v_mfma_f32_32x32x16_bf16 v[0:15], v[76:79], v[28:31], v[0:15]
	s_waitcnt lgkmcnt(0)
	v_mfma_f32_32x32x16_bf16 v[0:15], v[80:83], v[72:75], v[0:15]
	v_mfma_f32_32x32x16_bf16 v[0:15], v[84:87], v[178:181], v[0:15]
	ds_read_b128 v[84:87], v164 offset:62496
	s_nop 10
	v_cvt_pk_bf16_f32 v76, v0, v1
	v_cvt_pk_bf16_f32 v77, v2, v3
	ds_read_b128 v[0:3], v164 offset:62464
	v_cvt_pk_bf16_f32 v78, v4, v5
	v_cvt_pk_bf16_f32 v79, v6, v7
	v_cvt_pk_bf16_f32 v80, v8, v9
	v_cvt_pk_bf16_f32 v81, v10, v11
	v_cvt_pk_bf16_f32 v82, v12, v13
	v_cvt_pk_bf16_f32 v83, v14, v15
	s_waitcnt lgkmcnt(0)
	v_mfma_f32_32x32x16_bf16 v[0:15], v[0:3], v[170:173], 0
	v_mfma_f32_32x32x16_bf16 v[0:15], v[84:87], v[174:177], v[0:15]
	ds_read_b128 v[84:87], v164 offset:62528
	s_waitcnt lgkmcnt(0)
	v_mfma_f32_32x32x16_bf16 v[0:15], v[84:87], v[16:19], v[0:15]
	ds_read_b128 v[16:19], v164 offset:62560
	s_waitcnt lgkmcnt(0)
	v_mfma_f32_32x32x16_bf16 v[0:15], v[16:19], v[20:23], v[0:15]
	ds_read_b128 v[16:19], v164 offset:62592
	s_waitcnt lgkmcnt(0)
	v_mfma_f32_32x32x16_bf16 v[0:15], v[16:19], v[24:27], v[0:15]
	ds_read_b128 v[16:19], v164 offset:62624
	s_waitcnt lgkmcnt(0)
	v_mfma_f32_32x32x16_bf16 v[0:15], v[16:19], v[28:31], v[0:15]
	ds_read_b128 v[16:19], v164 offset:62656
	s_waitcnt lgkmcnt(0)
	v_mfma_f32_32x32x16_bf16 v[0:15], v[16:19], v[72:75], v[0:15]
	ds_read_b128 v[16:19], v164 offset:62688
	s_waitcnt lgkmcnt(0)
	v_mfma_f32_32x32x16_bf16 v[0:15], v[16:19], v[178:181], v[0:15]
	s_nop 11
	v_cndmask_b32_e64 v16, v0, 0, s[78:79]
	v_cndmask_b32_e64 v0, v16, v0, s[76:77]
	v_cndmask_b32_e64 v1, 0, v1, s[76:77]
	v_cndmask_b32_e64 v2, v2, 0, s[74:75]
	v_cndmask_b32_e64 v3, v3, 0, s[46:47]
	v_cvt_pk_bf16_f32 v84, v0, v1
	v_cvt_pk_bf16_f32 v85, v2, v3
	ds_read2_b64 v[0:3], v113 offset1:2
	ds_read2_b64 v[170:173], v113 offset0:4 offset1:6
	s_waitcnt lgkmcnt(1)
	v_mfma_f32_32x32x16_bf16 v[16:31], v[60:63], v[0:3], 0
	ds_read2_b64 v[0:3], v115 offset1:2
	ds_read2_b64 v[174:177], v115 offset0:4 offset1:6
	v_cndmask_b32_e64 v4, v4, 0, s[44:45]
	v_cndmask_b32_e64 v5, v5, 0, s[42:43]
	v_cndmask_b32_e64 v6, v6, 0, s[38:39]
	v_cndmask_b32_e64 v7, v7, 0, s[36:37]
	v_cndmask_b32_e64 v8, v8, 0, s[40:41]
	v_cndmask_b32_e64 v9, v9, 0, s[18:19]
	v_cndmask_b32_e64 v10, v10, 0, s[16:17]
	v_cndmask_b32_e64 v11, v11, 0, s[14:15]
	v_cndmask_b32_e64 v12, v12, 0, s[12:13]
	v_cndmask_b32_e64 v13, v13, 0, s[30:31]
	v_cndmask_b32_e64 v14, v14, 0, s[24:25]
	v_cndmask_b32_e64 v15, v15, 0, s[0:1]
	v_cvt_pk_bf16_f32 v86, v4, v5
	v_cvt_pk_bf16_f32 v87, v6, v7
	v_cvt_pk_bf16_f32 v72, v8, v9
	v_cvt_pk_bf16_f32 v73, v10, v11
	v_cvt_pk_bf16_f32 v74, v12, v13
	v_cvt_pk_bf16_f32 v75, v14, v15
	s_waitcnt lgkmcnt(1)
	v_mfma_f32_32x32x16_bf16 v[0:15], v[60:63], v[0:3], 0
	v_mfma_f32_32x32x16_bf16 v[16:31], v[56:59], v[170:173], v[16:31]
	s_waitcnt lgkmcnt(0)
	v_mfma_f32_32x32x16_bf16 v[0:15], v[56:59], v[174:177], v[0:15]
	ds_read2_b64 v[56:59], v113 offset0:8 offset1:10
	s_waitcnt lgkmcnt(0)
	v_mfma_f32_32x32x16_bf16 v[16:31], v[52:55], v[56:59], v[16:31]
	ds_read2_b64 v[56:59], v115 offset0:8 offset1:10
	s_waitcnt lgkmcnt(0)
	v_mfma_f32_32x32x16_bf16 v[0:15], v[52:55], v[56:59], v[0:15]
	ds_read2_b64 v[52:55], v113 offset0:12 offset1:14
	s_waitcnt lgkmcnt(0)
	v_mfma_f32_32x32x16_bf16 v[16:31], v[48:51], v[52:55], v[16:31]
	ds_read2_b64 v[52:55], v115 offset0:12 offset1:14
	s_waitcnt lgkmcnt(0)
	v_mfma_f32_32x32x16_bf16 v[0:15], v[48:51], v[52:55], v[0:15]
	ds_read2_b64 v[48:51], v113 offset0:16 offset1:18
	s_waitcnt lgkmcnt(0)
	v_mfma_f32_32x32x16_bf16 v[16:31], v[44:47], v[48:51], v[16:31]
	ds_read2_b64 v[48:51], v115 offset0:16 offset1:18
	s_waitcnt lgkmcnt(0)
	v_mfma_f32_32x32x16_bf16 v[0:15], v[44:47], v[48:51], v[0:15]
	ds_read2_b64 v[44:47], v113 offset0:20 offset1:22
	s_waitcnt lgkmcnt(0)
	v_mfma_f32_32x32x16_bf16 v[16:31], v[40:43], v[44:47], v[16:31]
	ds_read2_b64 v[44:47], v115 offset0:20 offset1:22
	s_waitcnt lgkmcnt(0)
	v_mfma_f32_32x32x16_bf16 v[0:15], v[40:43], v[44:47], v[0:15]
	ds_read2_b64 v[40:43], v113 offset0:24 offset1:26
	s_waitcnt lgkmcnt(0)
	v_mfma_f32_32x32x16_bf16 v[16:31], v[36:39], v[40:43], v[16:31]
	ds_read2_b64 v[40:43], v115 offset0:24 offset1:26
	s_waitcnt lgkmcnt(0)
	v_mfma_f32_32x32x16_bf16 v[0:15], v[36:39], v[40:43], v[0:15]
	ds_read2_b64 v[36:39], v113 offset0:28 offset1:30
	s_waitcnt lgkmcnt(0)
	v_mfma_f32_32x32x16_bf16 v[16:31], v[32:35], v[36:39], v[16:31]
	ds_read2_b64 v[36:39], v115 offset0:28 offset1:30
	s_waitcnt lgkmcnt(0)
	v_mfma_f32_32x32x16_bf16 v[0:15], v[32:35], v[36:39], v[0:15]
	ds_read_b64_tr_b16 v[32:33], v167 offset:8192
	ds_read_b64_tr_b16 v[34:35], v167 offset:12800
	ds_read_b64_tr_b16 v[36:37], v167 offset:17408
	ds_read_b64_tr_b16 v[38:39], v167 offset:22016
	s_waitcnt lgkmcnt(2)
	v_mfma_f32_32x32x16_bf16 v[0:15], v[32:35], v[76:79], v[0:15]
	s_waitcnt lgkmcnt(0)
	v_mfma_f32_32x32x16_bf16 v[0:15], v[36:39], v[80:83], v[0:15]
	v_mfma_f32_32x32x16_bf16 v[16:31], v[32:35], v[68:71], v[16:31]
	ds_read_b64_tr_b16 v[32:33], v167 offset:26624
	ds_read_b64_tr_b16 v[34:35], v167 offset:31232
	s_waitcnt lgkmcnt(0)
	v_mfma_f32_32x32x16_bf16 v[0:15], v[32:35], v[84:87], v[0:15]
	ds_read_b64_tr_b16 v[32:33], v167 offset:35840
	ds_read_b64_tr_b16 v[34:35], v167 offset:40448
	v_mfma_f32_32x32x16_bf16 v[16:31], v[36:39], v[64:67], v[16:31]
	s_waitcnt lgkmcnt(0)
	v_mfma_f32_32x32x16_bf16 v[0:15], v[32:35], v[72:75], v[0:15]
	s_nop 9
	v_mul_f32_e32 v32, v17, v17
	v_fmac_f32_e32 v32, v16, v16
	v_fmac_f32_e32 v32, v18, v18
	v_fmac_f32_e32 v32, v19, v19
	v_fmac_f32_e32 v32, v20, v20
	v_fmac_f32_e32 v32, v21, v21
	v_fmac_f32_e32 v32, v22, v22
	v_mul_f32_e32 v33, v1, v1
	v_fmac_f32_e32 v33, v0, v0
	v_fmac_f32_e32 v33, v2, v2
	v_fmac_f32_e32 v33, v3, v3
	v_fmac_f32_e32 v33, v4, v4
	v_fmac_f32_e32 v33, v5, v5
	v_fmac_f32_e32 v33, v6, v6
	v_fmac_f32_e32 v32, v23, v23
	v_fmac_f32_e32 v33, v7, v7
	v_fmac_f32_e32 v32, v24, v24
	v_fmac_f32_e32 v33, v8, v8
	v_fmac_f32_e32 v32, v25, v25
	v_fmac_f32_e32 v33, v9, v9
	v_fmac_f32_e32 v32, v26, v26
	v_fmac_f32_e32 v33, v10, v10
	v_fmac_f32_e32 v32, v27, v27
	v_fmac_f32_e32 v33, v11, v11
	v_fmac_f32_e32 v32, v28, v28
	v_fmac_f32_e32 v33, v12, v12
	v_fmac_f32_e32 v32, v29, v29
	v_fmac_f32_e32 v33, v13, v13
	v_fmac_f32_e32 v32, v30, v30
	v_fmac_f32_e32 v33, v14, v14
	v_fmac_f32_e32 v32, v31, v31
	v_fmac_f32_e32 v33, v15, v15
	ds_bpermute_b32 v34, v148, v32
	ds_bpermute_b32 v35, v148, v33
	s_mov_b64 s[0:1], exec
	v_readlane_b32 s24, v245, 44
	v_readlane_b32 s25, v245, 45
	s_and_b64 s[24:25], s[0:1], s[24:25]
	s_mov_b64 exec, s[24:25]
	s_cbranch_execz .LBB0_130
	s_waitcnt lgkmcnt(0)
	v_add_f32_e32 v33, v33, v35
	v_add_f32_e32 v32, v32, v34
	ds_write2_b32 v168, v32, v33 offset1:32
	s_branch .LBB0_130
